# P10 combine loop: counted vmcnt waits so that the next token's loads overlap the current token's compute
# speedup vs baseline: 1.0105x; 1.0008x over previous
.LBB0_45:
	s_or_b64 exec, exec, s[40:41]
	s_waitcnt vmcnt(8)
	v_cvt_f32_f16_sdwa v127, v84 dst_sel:DWORD dst_unused:UNUSED_PAD src0_sel:WORD_1
	v_cvt_f32_f16_e32 v126, v84
	v_cvt_f32_f16_sdwa v129, v76 dst_sel:DWORD dst_unused:UNUSED_PAD src0_sel:WORD_1
	v_cvt_f32_f16_e32 v128, v76
	v_lshlrev_b32_e32 v115, 16, v92
	v_lshlrev_b32_e32 v117, 16, v88
	v_and_b32_e32 v114, 0xffff0000, v92
	v_and_b32_e32 v116, 0xffff0000, v88
	v_pk_add_f32 v[114:115], v[116:117], v[114:115]
	v_and_b32_e32 v117, 0xffff0000, v80
	v_lshlrev_b32_e32 v116, 16, v80
	v_and_b32_e32 v125, 0xffff0000, v72
	v_lshlrev_b32_e32 v124, 16, v72
	v_pk_mul_f32 v[116:117], v[116:117], v[124:125]
	v_pk_add_f32 v[124:125], v[128:129], v[126:127]
	v_pk_mul_f32 v[116:117], v[24:25], v[116:117]
	v_pk_add_f32 v[124:125], v[124:125], -2.0 op_sel_hi:[1,0]
	v_lshlrev_b32_e32 v119, 16, v93
	v_pk_fma_f32 v[124:125], v[28:29], v[124:125], 2.0 op_sel_hi:[1,1,0]
	v_lshlrev_b32_e32 v121, 16, v89
	v_pk_mul_f32 v[116:117], v[116:117], v[124:125]
	v_and_b32_e32 v118, 0xffff0000, v93
	v_and_b32_e32 v120, 0xffff0000, v89
	v_add_f32_e32 v2, 0, v116
	v_add_f32_e32 v2, v117, v2
	v_pk_add_f32 v[116:117], v[120:121], v[118:119]
	v_cvt_f32_f16_sdwa v121, v85 dst_sel:DWORD dst_unused:UNUSED_PAD src0_sel:WORD_1
	v_cvt_f32_f16_e32 v120, v85
	v_cvt_f32_f16_sdwa v85, v77 dst_sel:DWORD dst_unused:UNUSED_PAD src0_sel:WORD_1
	v_cvt_f32_f16_e32 v84, v77
	v_and_b32_e32 v119, 0xffff0000, v81
	v_lshlrev_b32_e32 v118, 16, v81
	v_and_b32_e32 v81, 0xffff0000, v73
	v_lshlrev_b32_e32 v80, 16, v73
	v_pk_add_f32 v[76:77], v[84:85], v[120:121]
	v_pk_mul_f32 v[72:73], v[118:119], v[80:81]
	v_pk_add_f32 v[76:77], v[76:77], -2.0 op_sel_hi:[1,0]
	v_pk_mul_f32 v[72:73], v[26:27], v[72:73]
	v_pk_fma_f32 v[76:77], v[30:31], v[76:77], 2.0 op_sel_hi:[1,1,0]
	v_cvt_f32_f16_sdwa v81, v86 dst_sel:DWORD dst_unused:UNUSED_PAD src0_sel:WORD_1
	v_cvt_f32_f16_e32 v80, v86
	v_cvt_f32_f16_sdwa v85, v78 dst_sel:DWORD dst_unused:UNUSED_PAD src0_sel:WORD_1
	v_cvt_f32_f16_e32 v84, v78
	v_pk_mul_f32 v[72:73], v[72:73], v[76:77]
	v_and_b32_e32 v77, 0xffff0000, v74
	v_add_f32_e32 v2, v72, v2
	v_add_f32_e32 v2, v73, v2
	v_and_b32_e32 v73, 0xffff0000, v82
	v_lshlrev_b32_e32 v72, 16, v82
	v_lshlrev_b32_e32 v76, 16, v74
	v_pk_mul_f32 v[72:73], v[72:73], v[76:77]
	v_pk_add_f32 v[76:77], v[84:85], v[80:81]
	v_pk_mul_f32 v[72:73], v[16:17], v[72:73]
	v_pk_add_f32 v[76:77], v[76:77], -2.0 op_sel_hi:[1,0]
	v_cvt_f32_f16_sdwa v81, v87 dst_sel:DWORD dst_unused:UNUSED_PAD src0_sel:WORD_1
	v_pk_fma_f32 v[76:77], v[20:21], v[76:77], 2.0 op_sel_hi:[1,1,0]
	v_cvt_f32_f16_e32 v80, v87
	v_pk_mul_f32 v[72:73], v[72:73], v[76:77]
	v_cvt_f32_f16_e32 v82, v79
	v_add_f32_e32 v2, v72, v2
	v_add_f32_e32 v2, v73, v2
	v_and_b32_e32 v73, 0xffff0000, v83
	v_lshlrev_b32_e32 v72, 16, v83
	v_cvt_f32_f16_sdwa v83, v79 dst_sel:DWORD dst_unused:UNUSED_PAD src0_sel:WORD_1
	v_and_b32_e32 v77, 0xffff0000, v75
	v_lshlrev_b32_e32 v76, 16, v75
	v_pk_mul_f32 v[72:73], v[72:73], v[76:77]
	v_pk_add_f32 v[74:75], v[82:83], v[80:81]
	v_pk_mul_f32 v[72:73], v[18:19], v[72:73]
	v_pk_add_f32 v[74:75], v[74:75], -2.0 op_sel_hi:[1,0]
	v_add_f32_e32 v0, 0, v115
	v_pk_fma_f32 v[74:75], v[22:23], v[74:75], 2.0 op_sel_hi:[1,1,0]
	v_add_f32_e32 v0, v114, v0
	v_pk_mul_f32 v[72:73], v[72:73], v[74:75]
	v_lshlrev_b32_e32 v89, 16, v94
	v_add_f32_e32 v2, v72, v2
	v_add_f32_e32 v112, v73, v2
	ds_bpermute_b32 v122, v99, v112
	v_lshlrev_b32_e32 v93, 16, v90
	v_and_b32_e32 v88, 0xffff0000, v94
	v_and_b32_e32 v92, 0xffff0000, v90
	v_add_f32_e32 v0, v117, v0
	v_lshlrev_b32_e32 v113, 16, v91
	v_lshlrev_b32_e32 v123, 16, v95
	v_add_f32_e32 v0, v116, v0
	v_pk_add_f32 v[72:73], v[92:93], v[88:89]
	s_waitcnt lgkmcnt(0)
	v_pk_add_f32 v[74:75], v[112:113], v[122:123]
	v_add_f32_e32 v0, v73, v0
	v_and_b32_e32 v90, 0xffff0000, v95
	v_and_b32_e32 v94, 0xffff0000, v91
	v_add_f32_e32 v91, v72, v0
	v_mov_b32_e32 v95, v75
	v_pk_add_f32 v[76:77], v[94:95], v[90:91]
	ds_bpermute_b32 v80, v110, v74
	v_add_f32_e32 v0, v76, v77
	ds_bpermute_b32 v2, v99, v0
	v_pk_mov_b32 v[86:87], v[72:73], v[116:117] op_sel:[1,0]
	v_lshlrev_b32_e32 v106, 16, v71
	v_and_b32_e32 v92, 0xffff0000, v71
	v_and_b32_e32 v71, 0xffff0000, v64
	s_waitcnt lgkmcnt(0)
	v_add_f32_e32 v0, v0, v2
	ds_bpermute_b32 v2, v110, v0
	v_lshlrev_b32_e32 v73, 16, v65
	v_and_b32_e32 v91, 0xffff0000, v65
	v_lshlrev_b32_e32 v78, 16, v68
	v_lshlrev_b32_e32 v93, 16, v66
	s_waitcnt lgkmcnt(0)
	v_add_f32_e32 v0, v0, v2
	ds_bpermute_b32 v2, v111, v0
	v_and_b32_e32 v94, 0xffff0000, v67
	v_and_b32_e32 v68, 0xffff0000, v68
	v_lshlrev_b32_e32 v82, 16, v69
	v_lshlrev_b32_e32 v90, 16, v70
	s_waitcnt lgkmcnt(0)
	v_add_f32_e32 v2, v0, v2
	v_mul_f32_e32 v81, 0x3c800000, v2
	v_fmac_f32_e32 v114, 0xbc800000, v2
	v_fmamk_f32 v8, v2, 0xbc800000, v115
	v_mul_f32_e32 v10, v114, v114
	v_mov_b32_e32 v0, v81
	v_fmac_f32_e32 v10, v8, v8
	v_fmamk_f32 v77, v2, 0xbc800000, v117
	v_pk_add_f32 v[86:87], v[86:87], v[0:1] op_sel_hi:[1,0] neg_lo:[0,1] neg_hi:[0,1]
	v_fmac_f32_e32 v10, v77, v77
	v_pk_mul_f32 v[88:89], v[86:87], v[86:87]
	v_pk_add_f32 v[84:85], v[74:75], v[80:81] neg_lo:[0,1] neg_hi:[0,1]
	v_add_f32_e32 v0, v89, v10
	v_fmac_f32_e32 v72, 0xbc800000, v2
	v_add_f32_e32 v0, v88, v0
	v_mov_b32_e32 v88, v85
	v_mov_b32_e32 v89, v72
	v_pk_mul_f32 v[88:89], v[88:89], v[88:89]
	v_fmac_f32_e32 v76, 0xbc800000, v2
	v_add_f32_e32 v0, v89, v0
	v_add_f32_e32 v0, v88, v0
	v_fmac_f32_e32 v0, v76, v76
	ds_bpermute_b32 v2, v99, v0
	v_lshlrev_b32_e32 v10, 16, v64
	v_pk_add_f32 v[64:65], v[74:75], v[80:81]
	ds_bpermute_b32 v74, v111, v64
	v_and_b32_e32 v80, 0xffff0000, v66
	s_waitcnt lgkmcnt(1)
	v_add_f32_e32 v0, v0, v2
	ds_bpermute_b32 v2, v110, v0
	v_lshlrev_b32_e32 v81, 16, v67
	v_and_b32_e32 v88, 0xffff0000, v69
	v_and_b32_e32 v70, 0xffff0000, v70
	s_and_b64 s[0:1], exec, vcc
	s_waitcnt lgkmcnt(0)
	v_add_f32_e32 v0, v0, v2
	ds_bpermute_b32 v2, v111, v0
	s_or_b64 s[38:39], s[0:1], s[38:39]
	s_waitcnt lgkmcnt(0)
	v_add_f32_e32 v0, v0, v2
	v_fmamk_f32 v0, v0, 0x3c800000, v225
	v_rsq_f32_e32 v75, v0
	s_nop 0
	v_pk_add_f32 v[64:65], v[64:65], v[74:75]
	v_mul_f32_e32 v79, v8, v75
	v_pk_mul_f32 v[66:67], v[84:85], v[74:75]
	v_mov_b32_e32 v102, v64
	v_mov_b32_e32 v65, v67
	v_pk_mul_f32 v[66:67], v[102:103], v[78:79]
	v_mul_f32_e32 v69, v114, v75
	v_add_f32_e32 v0, v4, v67
	v_add_f32_e32 v0, v66, v0
	v_mul_f32_e32 v10, v0, v10
	v_mov_b32_e32 v0, v64
	v_pk_mul_f32 v[66:67], v[0:1], v[68:69]
	v_mul_f32_e32 v83, v77, v75
	v_add_f32_e32 v0, v5, v67
	v_mov_b32_e32 v104, v64
	v_add_f32_e32 v0, v66, v0
	v_pk_mul_f32 v[66:67], v[104:105], v[82:83]
	v_mul_f32_e32 v89, v87, v75
	v_add_f32_e32 v2, v6, v67
	v_add_f32_e32 v2, v66, v2
	v_mul_f32_e32 v68, v2, v73
	v_mov_b32_e32 v2, v64
	v_pk_mul_f32 v[66:67], v[2:3], v[88:89]
	v_mov_b32_e32 v108, v64
	v_add_f32_e32 v2, v7, v67
	v_add_f32_e32 v2, v66, v2
	v_mul_f32_e32 v2, v2, v91
	v_mul_f32_e32 v91, v86, v75
	v_pk_mul_f32 v[66:67], v[108:109], v[90:91]
	v_mul_f32_e32 v0, v0, v71
	v_add_f32_e32 v8, v12, v67
	v_add_f32_e32 v8, v66, v8
	v_mul_f32_e32 v69, v8, v93
	v_mul_f32_e32 v71, v72, v75
	v_mov_b32_e32 v8, v64
	v_pk_mul_f32 v[66:67], v[8:9], v[70:71]
	v_mul_f32_e32 v93, v76, v75
	v_add_f32_e32 v8, v13, v67
	v_add_f32_e32 v8, v66, v8
	v_pk_mul_f32 v[66:67], v[64:65], v[106:107]
	v_mul_f32_e32 v8, v8, v80
	v_add_f32_e32 v65, v14, v67
	v_add_f32_e32 v65, v66, v65
	v_mul_f32_e32 v67, v65, v81
	v_mov_b32_e32 v65, v11
	v_pk_mul_f32 v[64:65], v[64:65], v[92:93]
	v_add_f32_e32 v65, v15, v65
	v_add_f32_e32 v64, v64, v65
	v_mul_f32_e32 v70, v64, v94
	v_cvt_pk_bf16_f32 v64, v10, v0
	v_cvt_pk_bf16_f32 v65, v68, v2
	v_cvt_pk_bf16_f32 v66, v69, v8
	v_cvt_pk_bf16_f32 v67, v67, v70
	global_store_dwordx4 v[100:101], v[64:67], off
	v_lshl_add_u64 v[100:101], v[100:101], 0, s[36:37]
	s_waitcnt vmcnt(1)
	v_mov_b32_e32 v95, v39
	v_mov_b64_e32 v[78:79], v[62:63]
	v_mov_b64_e32 v[76:77], v[60:61]
	v_mov_b32_e32 v88, v32
	v_mov_b32_e32 v89, v33
	v_mov_b32_e32 v90, v34
	v_mov_b32_e32 v91, v35
	v_mov_b32_e32 v92, v36
	v_mov_b32_e32 v93, v37
	v_mov_b32_e32 v94, v38
	v_mov_b32_e32 v80, v40
	v_mov_b32_e32 v81, v41
	v_mov_b32_e32 v82, v42
	v_mov_b32_e32 v83, v43
	v_mov_b32_e32 v72, v44
	v_mov_b32_e32 v73, v45
	v_mov_b32_e32 v74, v46
	v_mov_b32_e32 v75, v47
	v_mov_b32_e32 v68, v48
	v_mov_b32_e32 v69, v49
	v_mov_b32_e32 v70, v50
	v_mov_b32_e32 v71, v51
	v_mov_b32_e32 v64, v52
	v_mov_b32_e32 v65, v53
	v_mov_b32_e32 v66, v54
	v_mov_b32_e32 v67, v55
	v_mov_b32_e32 v84, v56
	v_mov_b32_e32 v85, v57
	v_mov_b32_e32 v86, v58
	v_mov_b32_e32 v87, v59
	s_andn2_b64 exec, exec, s[38:39]
	s_cbranch_execz .LBB0_48
